# P0 lane-block merge: row A defers its 4 f-gate log-sigmoids, row B's lane block runs one 8-lane instance (DPP row_shr:4) for both rows
# speedup vs baseline: 1.0003x; 1.0003x over previous
.LBB0_26:
	v_add_u32_e32 v18, 0xffffc000, v42
	v_cmp_gt_i32_e32 vcc, s25, v42
	v_mov_b32_e32 v29, s54
	v_mov_b32_e32 v32, s52
	v_cndmask_b32_e32 v19, 0, v43, vcc
	v_cndmask_b32_e32 v18, v18, v42, vcc
	s_waitcnt lgkmcnt(0)
	v_cndmask_b32_e32 v21, v72, v73, vcc
	v_cndmask_b32_e32 v20, v29, v32, vcc
	v_lshlrev_b64 v[18:19], 12, v[18:19]
	v_lshl_add_u64 v[18:19], v[20:21], 0, v[18:19]
	v_lshl_add_u64 v[18:19], v[18:19], 0, v[44:45]
	global_load_dwordx4 v[56:59], v[18:19], off
	global_load_dwordx4 v[60:63], v[18:19], off offset:1024
	global_load_dwordx4 v[34:37], v[18:19], off offset:3072
	global_load_dwordx4 v[38:41], v[18:19], off offset:2048
	s_waitcnt vmcnt(3)
	v_pk_mul_f32 v[18:19], v[58:59], v[58:59]
	v_pk_mul_f32 v[20:21], v[56:57], v[56:57]
	s_waitcnt vmcnt(2)
	v_pk_mul_f32 v[22:23], v[62:63], v[62:63]
	v_pk_mul_f32 v[24:25], v[60:61], v[60:61]
	v_pk_mov_b32 v[30:31], v[20:21], v[18:19] op_sel:[1,0]
	v_mov_b32_e32 v21, v19
	v_pk_mov_b32 v[18:19], v[24:25], v[22:23] op_sel:[1,0]
	v_mov_b32_e32 v25, v23
	s_waitcnt vmcnt(0)
	v_mul_f32_e32 v26, v39, v39
	v_mul_f32_e32 v28, v41, v41
	v_pk_add_f32 v[20:21], v[30:31], v[20:21]
	v_pk_add_f32 v[18:19], v[18:19], v[24:25]
	v_mul_f32_e32 v33, v34, v34
	v_mul_f32_e32 v54, v35, v35
	v_mul_f32_e32 v55, v36, v36
	v_mul_f32_e32 v64, v37, v37
	v_pk_fma_f32 v[22:23], v[38:39], v[38:39], v[26:27] op_sel_hi:[1,1,0]
	v_pk_fma_f32 v[26:27], v[40:41], v[40:41], v[28:29] op_sel_hi:[1,1,0]
	v_pk_add_f32 v[20:21], v[20:21], v[20:21] op_sel:[0,1] op_sel_hi:[1,0]
	v_pk_add_f32 v[18:19], v[18:19], v[18:19] op_sel:[0,1] op_sel_hi:[1,0]
	v_mov_b32_e32 v23, v55
	v_mov_b32_e32 v27, v64
	v_mov_b32_e32 v21, v33
	v_mov_b32_e32 v19, v54
	v_pk_add_f32 v[22:23], v[22:23], v[26:27]
	v_pk_add_f32 v[18:19], v[20:21], v[18:19]
	v_add_u32_e32 v20, s33, v42
	v_pk_add_f32 v[18:19], v[18:19], v[22:23]
	v_cmp_gt_i32_e64 s[4:5], s24, v20
	v_add_f32_e32 v18, v18, v19
	ds_bpermute_b32 v19, v66, v18
	v_cndmask_b32_e64 v20, v42, v20, s[4:5]
	v_add_u32_e32 v25, 0xffffc000, v20
	v_mov_b32_e32 v21, s55
	v_mov_b32_e32 v24, s53
	s_waitcnt lgkmcnt(0)
	v_add_f32_e32 v18, v18, v19
	ds_bpermute_b32 v19, v67, v18
	s_waitcnt lgkmcnt(0)
	v_add_f32_e32 v22, v18, v19
	ds_bpermute_b32 v23, v68, v22
	v_lshl_add_u64 v[18:19], s[74:75], 0, v[50:51]
	v_add_co_u32_e32 v54, vcc, s29, v18
	v_ashrrev_i32_e32 v18, 31, v20
	s_waitcnt lgkmcnt(0)
	v_add_f32_e32 v22, v22, v23
	ds_bpermute_b32 v23, v69, v22
	v_addc_co_u32_e32 v55, vcc, 0, v19, vcc
	v_cmp_gt_i32_e32 vcc, s25, v20
	s_waitcnt lgkmcnt(0)
	v_add_f32_e32 v22, v22, v23
	ds_bpermute_b32 v23, v70, v22
	v_cndmask_b32_e32 v19, 0, v18, vcc
	v_cndmask_b32_e32 v18, v25, v20, vcc
	v_cndmask_b32_e32 v21, v21, v24, vcc
	v_cndmask_b32_e32 v20, v29, v32, vcc
	s_waitcnt lgkmcnt(0)
	v_add_f32_e32 v22, v22, v23
	ds_bpermute_b32 v23, v71, v22
	v_lshlrev_b64 v[18:19], 12, v[18:19]
	v_lshl_add_u64 v[18:19], v[20:21], 0, v[18:19]
	v_lshl_add_u64 v[18:19], v[18:19], 0, v[44:45]
	s_waitcnt lgkmcnt(0)
	v_add_f32_e32 v20, v22, v23
	v_fmamk_f32 v20, v20, 0x3a800000, v74
	v_mul_f32_e32 v21, 0x4b800000, v20
	v_cmp_gt_f32_e32 vcc, s28, v20
	s_nop 1
	v_cndmask_b32_e32 v20, v20, v21, vcc
	v_rsq_f32_e32 v64, v20
	global_load_dwordx4 v[30:33], v[18:19], off
	global_load_dwordx4 v[26:29], v[18:19], off offset:1024
	global_load_dwordx4 v[22:25], v[18:19], off offset:2048
	s_nop 0
	global_load_dwordx4 v[18:21], v[18:19], off offset:3072
	v_mul_f32_e32 v65, 0x45800000, v64
	v_cndmask_b32_e32 v64, v64, v65, vcc
	v_pk_mul_f32 v[56:57], v[56:57], v[64:65] op_sel_hi:[1,0]
	v_pk_mul_f32 v[58:59], v[58:59], v[64:65] op_sel_hi:[1,0]
	v_pk_mul_f32 v[38:39], v[38:39], v[64:65] op_sel_hi:[1,0]
	v_pk_mul_f32 v[34:35], v[34:35], v[64:65] op_sel_hi:[1,0]
	v_pk_mul_f32 v[60:61], v[60:61], v[64:65] op_sel_hi:[1,0]
	v_pk_mul_f32 v[78:79], v[62:63], v[64:65] op_sel_hi:[1,0]
	v_pk_mul_f32 v[40:41], v[40:41], v[64:65] op_sel_hi:[1,0]
	v_pk_mul_f32 v[36:37], v[36:37], v[64:65] op_sel_hi:[1,0]
	v_pk_mul_f32 v[62:63], v[4:5], v[58:59]
	v_pk_mul_f32 v[64:65], v[2:3], v[56:57]
	v_pk_mul_f32 v[56:57], v[10:11], v[38:39]
	v_pk_mul_f32 v[38:39], v[14:15], v[34:35]
	v_cvt_pk_bf16_f32 v34, v64, v65
	v_cvt_pk_bf16_f32 v35, v62, v63
	v_pk_mul_f32 v[58:59], v[8:9], v[78:79]
	v_pk_mul_f32 v[60:61], v[6:7], v[60:61]
	global_store_dwordx2 v[54:55], v[34:35], off
	v_cvt_pk_bf16_f32 v34, v60, v61
	v_cvt_pk_bf16_f32 v35, v58, v59
	v_pk_mul_f32 v[40:41], v[12:13], v[40:41]
	global_store_dwordx2 v[54:55], v[34:35], off offset:512
	v_cvt_pk_bf16_f32 v34, v56, v57
	v_cvt_pk_bf16_f32 v35, v40, v41
	v_pk_mul_f32 v[36:37], v[16:17], v[36:37]
	global_store_dwordx2 v[54:55], v[34:35], off offset:1024
	v_cvt_pk_bf16_f32 v34, v38, v39
	v_cvt_pk_bf16_f32 v35, v36, v37
	ds_read_b128 v[78:81], v1
	ds_read_b128 v[82:85], v1 offset:1024
	ds_read_b128 v[86:89], v1 offset:2048
	ds_read_b128 v[90:93], v1 offset:3072
	ds_read_b128 v[94:97], v1 offset:4096
	ds_read_b128 v[98:101], v1 offset:5120
	ds_read_b128 v[102:105], v1 offset:6144
	ds_read_b128 v[106:109], v1 offset:7168
	s_waitcnt lgkmcnt(7)
	v_mul_f32_e32 v77, v65, v79
	v_mul_f32_e32 v79, v63, v81
	s_waitcnt lgkmcnt(6)
	v_mul_f32_e32 v81, v61, v83
	v_mul_f32_e32 v83, v59, v85
	v_fmac_f32_e32 v77, v64, v78
	v_fmac_f32_e32 v79, v62, v80
	s_waitcnt lgkmcnt(5)
	v_mul_f32_e32 v85, v57, v87
	v_mul_f32_e32 v87, v41, v89
	v_fmac_f32_e32 v81, v60, v82
	v_fmac_f32_e32 v83, v58, v84
	v_add_f32_e32 v77, v77, v79
	s_waitcnt lgkmcnt(4)
	v_mul_f32_e32 v89, v39, v91
	v_mul_f32_e32 v91, v37, v93
	v_fmac_f32_e32 v85, v56, v86
	v_fmac_f32_e32 v87, v40, v88
	v_add_f32_e32 v78, v81, v83
	v_add_f32_e32 v77, 0, v77
	v_fmac_f32_e32 v89, v38, v90
	v_fmac_f32_e32 v91, v36, v92
	v_add_f32_e32 v79, v85, v87
	v_add_f32_e32 v77, v77, v78
	s_waitcnt lgkmcnt(3)
	v_mul_f32_e32 v93, v65, v95
	v_mul_f32_e32 v95, v63, v97
	v_add_f32_e32 v80, v89, v91
	v_add_f32_e32 v77, v77, v79
	s_waitcnt lgkmcnt(2)
	v_mul_f32_e32 v97, v61, v99
	v_mul_f32_e32 v99, v59, v101
	v_fmac_f32_e32 v93, v64, v94
	v_fmac_f32_e32 v95, v62, v96
	v_add_f32_e32 v77, v77, v80
	v_fmac_f32_e32 v97, v60, v98
	v_fmac_f32_e32 v99, v58, v100
	ds_bpermute_b32 v78, v66, v77
	v_add_f32_e32 v79, v93, v95
	v_add_f32_e32 v80, v97, v99
	v_add_f32_e32 v79, 0, v79
	s_waitcnt lgkmcnt(2)
	v_mul_f32_e32 v101, v57, v103
	v_add_f32_e32 v79, v79, v80
	v_mul_f32_e32 v80, v41, v105
	v_fmac_f32_e32 v101, v56, v102
	v_fmac_f32_e32 v80, v40, v104
	v_add_f32_e32 v80, v101, v80
	s_waitcnt lgkmcnt(0)
	v_add_f32_e32 v77, v77, v78
	v_add_f32_e32 v79, v79, v80
	v_mul_f32_e32 v80, v39, v107
	v_mul_f32_e32 v81, v37, v109
	ds_bpermute_b32 v78, v67, v77
	v_fmac_f32_e32 v80, v38, v106
	v_fmac_f32_e32 v81, v36, v108
	v_add_f32_e32 v80, v80, v81
	v_add_f32_e32 v79, v79, v80
	ds_bpermute_b32 v80, v66, v79
	s_waitcnt lgkmcnt(1)
	v_add_f32_e32 v77, v77, v78
	ds_bpermute_b32 v78, v68, v77
	global_store_dwordx2 v[54:55], v[34:35], off offset:1536
	s_waitcnt lgkmcnt(1)
	v_add_f32_e32 v82, v79, v80
	ds_bpermute_b32 v83, v67, v82
	s_waitcnt lgkmcnt(1)
	v_add_f32_e32 v77, v77, v78
	ds_read_b128 v[78:81], v1 offset:8192
	ds_bpermute_b32 v86, v69, v77
	s_waitcnt lgkmcnt(2)
	v_add_f32_e32 v87, v82, v83
	ds_read_b128 v[82:85], v1 offset:9216
	s_waitcnt lgkmcnt(2)
	v_mul_f32_e32 v79, v65, v79
	v_fmac_f32_e32 v79, v64, v78
	v_mul_f32_e32 v78, v63, v81
	v_fmac_f32_e32 v78, v62, v80
	v_add_f32_e32 v78, v79, v78
	s_waitcnt lgkmcnt(0)
	v_mul_f32_e32 v83, v61, v83
	v_add_f32_e32 v89, 0, v78
	v_fmac_f32_e32 v83, v60, v82
	v_mul_f32_e32 v82, v59, v85
	ds_read_b128 v[78:81], v1 offset:10240
	v_fmac_f32_e32 v82, v58, v84
	v_add_f32_e32 v82, v83, v82
	v_add_f32_e32 v89, v89, v82
	ds_read_b128 v[82:85], v1 offset:11264
	s_waitcnt lgkmcnt(1)
	v_mul_f32_e32 v79, v57, v79
	v_fmac_f32_e32 v79, v56, v78
	v_mul_f32_e32 v78, v41, v81
	v_fmac_f32_e32 v78, v40, v80
	v_add_f32_e32 v78, v79, v78
	s_waitcnt lgkmcnt(0)
	v_mul_f32_e32 v79, v39, v83
	v_mul_f32_e32 v80, v37, v85
	v_fmac_f32_e32 v79, v38, v82
	v_fmac_f32_e32 v80, v36, v84
	v_add_f32_e32 v78, v89, v78
	v_add_f32_e32 v79, v79, v80
	v_add_f32_e32 v78, v78, v79
	ds_bpermute_b32 v88, v68, v87
	ds_bpermute_b32 v79, v66, v78
	v_add_f32_e32 v77, v77, v86
	ds_bpermute_b32 v80, v70, v77
	s_waitcnt lgkmcnt(2)
	v_add_f32_e32 v84, v87, v88
	s_waitcnt lgkmcnt(1)
	v_add_f32_e32 v79, v78, v79
	ds_bpermute_b32 v85, v69, v84
	ds_bpermute_b32 v86, v67, v79
	s_waitcnt lgkmcnt(2)
	v_add_f32_e32 v77, v77, v80
	ds_read_b128 v[80:83], v1 offset:12288
	ds_bpermute_b32 v78, v71, v77
	s_waitcnt lgkmcnt(3)
	v_add_f32_e32 v88, v84, v85
	s_waitcnt lgkmcnt(2)
	v_add_f32_e32 v79, v79, v86
	ds_read_b128 v[84:87], v1 offset:13312
	s_waitcnt lgkmcnt(2)
	v_mul_f32_e32 v81, v65, v81
	v_fmac_f32_e32 v81, v64, v80
	v_mul_f32_e32 v80, v63, v83
	v_fmac_f32_e32 v80, v62, v82
	v_add_f32_e32 v80, v81, v80
	s_waitcnt lgkmcnt(0)
	v_mul_f32_e32 v85, v61, v85
	v_add_f32_e32 v90, 0, v80
	v_fmac_f32_e32 v85, v60, v84
	v_mul_f32_e32 v84, v59, v87
	ds_read_b128 v[80:83], v1 offset:14336
	v_fmac_f32_e32 v84, v58, v86
	v_add_f32_e32 v84, v85, v84
	v_add_f32_e32 v90, v90, v84
	ds_read_b128 v[84:87], v1 offset:15360
	s_waitcnt lgkmcnt(1)
	v_mul_f32_e32 v81, v57, v81
	v_fmac_f32_e32 v81, v56, v80
	v_mul_f32_e32 v80, v41, v83
	v_fmac_f32_e32 v80, v40, v82
	v_add_f32_e32 v80, v81, v80
	s_waitcnt lgkmcnt(0)
	v_mul_f32_e32 v85, v39, v85
	v_add_f32_e32 v90, v90, v80
	v_fmac_f32_e32 v85, v38, v84
	v_mul_f32_e32 v84, v37, v87
	ds_read_b128 v[80:83], v1 offset:16384
	v_fmac_f32_e32 v84, v36, v86
	v_add_f32_e32 v84, v85, v84
	v_add_f32_e32 v90, v90, v84
	ds_read_b128 v[84:87], v1 offset:17408
	s_waitcnt lgkmcnt(1)
	v_mul_f32_e32 v81, v65, v81
	v_fmac_f32_e32 v81, v64, v80
	v_mul_f32_e32 v80, v63, v83
	v_fmac_f32_e32 v80, v62, v82
	v_add_f32_e32 v80, v81, v80
	s_waitcnt lgkmcnt(0)
	v_mul_f32_e32 v85, v61, v85
	v_add_f32_e32 v92, 0, v80
	v_fmac_f32_e32 v85, v60, v84
	v_mul_f32_e32 v84, v59, v87
	ds_read_b128 v[80:83], v1 offset:18432
	v_fmac_f32_e32 v84, v58, v86
	v_add_f32_e32 v84, v85, v84
	v_add_f32_e32 v92, v92, v84
	ds_read_b128 v[84:87], v1 offset:19456
	s_waitcnt lgkmcnt(1)
	v_mul_f32_e32 v81, v57, v81
	v_fmac_f32_e32 v81, v56, v80
	v_mul_f32_e32 v80, v41, v83
	ds_bpermute_b32 v91, v66, v90
	v_fmac_f32_e32 v80, v40, v82
	v_add_f32_e32 v80, v81, v80
	s_waitcnt lgkmcnt(1)
	v_mul_f32_e32 v81, v39, v85
	v_mul_f32_e32 v82, v37, v87
	v_fmac_f32_e32 v81, v38, v84
	v_fmac_f32_e32 v82, v36, v86
	v_add_f32_e32 v80, v92, v80
	v_add_f32_e32 v81, v81, v82
	v_add_f32_e32 v80, v80, v81
	ds_bpermute_b32 v81, v66, v80
	s_waitcnt lgkmcnt(1)
	v_add_f32_e32 v83, v90, v91
	ds_bpermute_b32 v84, v67, v83
	ds_bpermute_b32 v89, v68, v79
	ds_bpermute_b32 v82, v70, v88
	s_waitcnt lgkmcnt(3)
	v_add_f32_e32 v80, v80, v81
	ds_bpermute_b32 v81, v67, v80
	s_waitcnt lgkmcnt(3)
	v_add_f32_e32 v83, v83, v84
	ds_bpermute_b32 v84, v68, v83
	s_waitcnt lgkmcnt(3)
	v_add_f32_e32 v85, v79, v89
	ds_bpermute_b32 v86, v69, v85
	s_waitcnt lgkmcnt(2)
	v_add_f32_e32 v80, v80, v81
	ds_bpermute_b32 v81, v68, v80
	s_waitcnt lgkmcnt(2)
	v_add_f32_e32 v83, v83, v84
	ds_bpermute_b32 v84, v69, v83
	s_waitcnt lgkmcnt(2)
	v_add_f32_e32 v85, v85, v86
	ds_bpermute_b32 v86, v70, v85
	s_waitcnt lgkmcnt(2)
	v_add_f32_e32 v81, v80, v81
	ds_bpermute_b32 v87, v69, v81
	s_waitcnt lgkmcnt(2)
	v_add_f32_e32 v84, v83, v84
	v_add_f32_e32 v79, v88, v82
	ds_bpermute_b32 v88, v70, v84
	s_waitcnt lgkmcnt(2)
	v_add_f32_e32 v80, v85, v86
	s_waitcnt lgkmcnt(1)
	v_add_f32_e32 v85, v81, v87
	ds_bpermute_b32 v87, v70, v85
	ds_read_b128 v[92:95], v1 offset:21504
	s_waitcnt lgkmcnt(2)
	v_add_f32_e32 v81, v84, v88
	ds_read_b128 v[88:91], v1 offset:20480
	ds_bpermute_b32 v82, v71, v79
	s_waitcnt lgkmcnt(3)
	v_add_f32_e32 v84, v85, v87
	s_waitcnt lgkmcnt(2)
	v_mul_f32_e32 v93, v61, v93
	v_fmac_f32_e32 v93, v60, v92
	s_waitcnt lgkmcnt(1)
	v_mul_f32_e32 v87, v65, v89
	v_fmac_f32_e32 v87, v64, v88
	v_mul_f32_e32 v88, v63, v91
	v_fmac_f32_e32 v88, v62, v90
	v_mul_f32_e32 v92, v59, v95
	v_add_f32_e32 v87, v87, v88
	ds_read_b128 v[88:91], v1 offset:22528
	v_fmac_f32_e32 v92, v58, v94
	v_add_f32_e32 v87, 0, v87
	v_add_f32_e32 v92, v93, v92
	v_add_f32_e32 v87, v87, v92
	ds_read_b128 v[92:95], v1 offset:23552
	s_waitcnt lgkmcnt(1)
	v_mul_f32_e32 v89, v57, v89
	v_fmac_f32_e32 v89, v56, v88
	v_mul_f32_e32 v88, v41, v91
	v_fmac_f32_e32 v88, v40, v90
	s_waitcnt lgkmcnt(0)
	v_mul_f32_e32 v93, v39, v93
	v_add_f32_e32 v88, v89, v88
	v_fmac_f32_e32 v93, v38, v92
	v_mul_f32_e32 v92, v37, v95
	v_add_f32_e32 v87, v87, v88
	v_fmac_f32_e32 v92, v36, v94
	ds_read_b128 v[88:91], v1 offset:24576
	v_add_f32_e32 v92, v93, v92
	v_add_f32_e32 v87, v87, v92
	ds_read_b128 v[92:95], v1 offset:25600
	ds_bpermute_b32 v96, v66, v87
	s_waitcnt lgkmcnt(2)
	v_mul_f32_e32 v89, v65, v89
	v_fmac_f32_e32 v89, v64, v88
	v_mul_f32_e32 v88, v63, v91
	v_fmac_f32_e32 v88, v62, v90
	s_waitcnt lgkmcnt(1)
	v_mul_f32_e32 v93, v61, v93
	v_add_f32_e32 v88, v89, v88
	v_fmac_f32_e32 v93, v60, v92
	v_mul_f32_e32 v92, v59, v95
	v_add_f32_e32 v97, 0, v88
	ds_read_b128 v[88:91], v1 offset:26624
	v_fmac_f32_e32 v92, v58, v94
	v_add_f32_e32 v92, v93, v92
	v_add_f32_e32 v97, v97, v92
	ds_read_b128 v[92:95], v1 offset:27648
	s_waitcnt lgkmcnt(1)
	v_mul_f32_e32 v89, v57, v89
	v_fmac_f32_e32 v89, v56, v88
	v_mul_f32_e32 v88, v41, v91
	v_fmac_f32_e32 v88, v40, v90
	s_waitcnt lgkmcnt(0)
	v_mul_f32_e32 v93, v39, v93
	v_add_f32_e32 v88, v89, v88
	v_fmac_f32_e32 v93, v38, v92
	v_mul_f32_e32 v92, v37, v95
	v_add_f32_e32 v97, v97, v88
	v_fmac_f32_e32 v92, v36, v94
	ds_read_b128 v[88:91], v1 offset:28672
	v_add_f32_e32 v92, v93, v92
	v_add_f32_e32 v97, v97, v92
	ds_read_b128 v[92:95], v1 offset:29696
	ds_bpermute_b32 v98, v66, v97
	s_waitcnt lgkmcnt(2)
	v_mul_f32_e32 v65, v65, v89
	v_mul_f32_e32 v63, v63, v91
	v_fmac_f32_e32 v65, v64, v88
	v_fmac_f32_e32 v63, v62, v90
	v_add_f32_e32 v62, v65, v63
	s_waitcnt lgkmcnt(1)
	v_mul_f32_e32 v65, v61, v93
	v_add_f32_e32 v64, 0, v62
	v_fmac_f32_e32 v65, v60, v92
	ds_read_b128 v[60:63], v1 offset:30720
	ds_read_b128 v[88:91], v1 offset:31744
	v_mul_f32_e32 v59, v59, v95
	v_fmac_f32_e32 v59, v58, v94
	v_add_f32_e32 v58, v65, v59
	s_waitcnt lgkmcnt(1)
	v_mul_f32_e32 v57, v57, v61
	v_mul_f32_e32 v41, v41, v63
	v_fmac_f32_e32 v57, v56, v60
	v_fmac_f32_e32 v41, v40, v62
	s_waitcnt lgkmcnt(0)
	v_mul_f32_e32 v39, v39, v89
	v_mul_f32_e32 v37, v37, v91
	v_add_f32_e32 v58, v64, v58
	v_add_f32_e32 v40, v57, v41
	v_fmac_f32_e32 v39, v38, v88
	v_fmac_f32_e32 v37, v36, v90
	v_add_f32_e32 v40, v58, v40
	v_add_f32_e32 v36, v39, v37
	v_add_f32_e32 v36, v40, v36
	ds_bpermute_b32 v37, v66, v36
	v_add_f32_e32 v38, v87, v96
	v_add_f32_e32 v40, v97, v98
	ds_bpermute_b32 v39, v67, v38
	ds_bpermute_b32 v41, v67, v40
	s_waitcnt lgkmcnt(2)
	v_add_f32_e32 v36, v36, v37
	ds_bpermute_b32 v37, v67, v36
	ds_bpermute_b32 v83, v71, v80
	s_waitcnt lgkmcnt(3)
	v_add_f32_e32 v38, v38, v39
	s_waitcnt lgkmcnt(2)
	v_add_f32_e32 v40, v40, v41
	ds_bpermute_b32 v39, v68, v38
	s_waitcnt lgkmcnt(2)
	v_add_f32_e32 v36, v36, v37
	ds_bpermute_b32 v41, v68, v40
	ds_bpermute_b32 v37, v68, v36
	ds_bpermute_b32 v86, v71, v81
	s_waitcnt lgkmcnt(3)
	v_add_f32_e32 v38, v38, v39
	ds_bpermute_b32 v39, v69, v38
	s_waitcnt lgkmcnt(3)
	v_add_f32_e32 v40, v40, v41
	s_waitcnt lgkmcnt(2)
	v_add_f32_e32 v36, v36, v37
	ds_bpermute_b32 v41, v69, v40
	ds_bpermute_b32 v37, v69, v36
	s_waitcnt lgkmcnt(2)
	v_add_f32_e32 v38, v38, v39
	ds_bpermute_b32 v39, v70, v38
	ds_bpermute_b32 v85, v71, v84
	s_waitcnt lgkmcnt(3)
	v_add_f32_e32 v56, v40, v41
	s_waitcnt lgkmcnt(2)
	v_add_f32_e32 v36, v36, v37
	ds_bpermute_b32 v57, v70, v56
	ds_bpermute_b32 v37, v70, v36
	s_waitcnt lgkmcnt(3)
	v_add_f32_e32 v40, v38, v39
	ds_bpermute_b32 v41, v71, v40
	s_waitcnt lgkmcnt(2)
	v_add_f32_e32 v38, v56, v57
	s_waitcnt lgkmcnt(1)
	v_add_f32_e32 v36, v36, v37
	ds_bpermute_b32 v39, v71, v38
	ds_bpermute_b32 v37, v71, v36
	s_and_saveexec_b64 s[26:27], s[68:69]
	s_waitcnt vmcnt(4)
	s_cbranch_execz .LBB0_28
	v_readlane_b32 s36, v254, 5
	v_readlane_b32 s37, v254, 6
	v_lshl_add_u64 v[34:35], s[74:75], 0, v[52:53]
	v_add_f32_e32 v55, v77, v78
	v_add_co_u32_e32 v34, vcc, 0x26a8000, v34
	v_readlane_b32 s38, v254, 7
	s_nop 0
	v_addc_co_u32_e32 v35, vcc, 0, v35, vcc
	v_readlane_b32 s39, v254, 8
	s_waitcnt lgkmcnt(2)
	v_add_f32_e32 v40, v40, v41
	s_waitcnt lgkmcnt(1)
	v_add_f32_e32 v38, v38, v39
	s_waitcnt lgkmcnt(0)
	v_add_f32_e32 v36, v36, v37
	v_readlane_b32 s40, v254, 9
	v_readlane_b32 s41, v254, 10
	v_readlane_b32 s42, v254, 11
	v_readlane_b32 s43, v254, 12
	v_readlane_b32 s44, v254, 13
	v_readlane_b32 s45, v254, 14
	v_readlane_b32 s46, v254, 15
	v_readlane_b32 s47, v254, 16
	v_readlane_b32 s48, v254, 17
	v_readlane_b32 s49, v254, 18
	v_readlane_b32 s50, v254, 19
	v_readlane_b32 s51, v254, 20
	v_add_f32_e32 v56, v79, v82
	v_add_f32_e32 v57, v80, v83
	v_add_f32_e32 v58, v81, v86
	v_cndmask_b32_e64 v55, v55, v56, s[18:19]
	v_cndmask_b32_e64 v55, v55, v57, s[20:21]
	v_cndmask_b32_e64 v55, v55, v58, s[22:23]
	v_add_f32_e32 v54, v110, v55
	v_add_co_u32_e32 v34, vcc, v112, v34
	s_nop 1
	v_addc_co_u32_e32 v35, vcc, 0, v35, vcc
	global_store_dword v[34:35], v54, off
	v_add_f32_e32 v55, v84, v85
	v_cndmask_b32_e64 v55, v55, v40, s[18:19]
	v_cndmask_b32_e64 v55, v55, v38, s[20:21]
	v_cndmask_b32_e64 v55, v55, v36, s[22:23]
	v_add_f32_e32 v54, v111, v55
	s_and_b64 vcc, exec, s[4:5]
	s_cbranch_scc0 .Lp0_fnow
	v_mov_b32_e32 v113, v54
	v_mov_b32_e32 v114, v34
	v_mov_b32_e32 v115, v35
	s_branch .LBB0_28
.Lp0_fnow:
	v_mul_f32_e64 v55, |v54|, s30
	v_fma_f32 v56, |v54|, s30, -v55
	v_rndne_f32_e32 v57, v55
	v_fma_f32 v56, |v54|, s31, v56
	v_sub_f32_e32 v55, v55, v57
	v_add_f32_e32 v55, v55, v56
	v_cvt_i32_f32_e32 v57, v57
	v_exp_f32_e32 v55, v55
	v_cmp_ngt_f32_e64 vcc, |v54|, s34
	v_min_f32_e32 v56, 0, v54
	v_ldexp_f32 v55, v55, v57
	v_cndmask_b32_e32 v55, 0, v55, vcc
	v_cmp_nlt_f32_e64 vcc, |v54|, s35
	s_nop 1
	v_cndmask_b32_e32 v57, v76, v55, vcc
	v_add_f32_e32 v58, 1.0, v57
	v_add_f32_e32 v59, -1.0, v58
	v_frexp_mant_f32_e32 v60, v58
	v_cvt_f64_f32_e32 v[54:55], v58
	v_sub_f32_e32 v61, v59, v58
	v_frexp_exp_i32_f64_e32 v54, v[54:55]
	v_cmp_gt_f32_e32 vcc, s65, v60
	v_sub_f32_e32 v59, v57, v59
	v_add_f32_e32 v55, 1.0, v61
	v_subbrev_co_u32_e32 v54, vcc, 0, v54, vcc
	v_add_f32_e32 v55, v59, v55
	v_sub_u32_e32 v59, 0, v54
	v_cvt_f32_i32_e32 v54, v54
	v_ldexp_f32 v58, v58, v59
	v_ldexp_f32 v55, v55, v59
	v_add_f32_e32 v59, -1.0, v58
	v_add_f32_e32 v60, 1.0, v58
	v_add_f32_e32 v61, 1.0, v59
	v_add_f32_e32 v62, -1.0, v60
	v_sub_f32_e32 v61, v58, v61
	v_sub_f32_e32 v58, v58, v62
	v_mul_f32_e32 v62, 0x3f317218, v54
	v_add_f32_e32 v61, v55, v61
	v_add_f32_e32 v55, v55, v58
	v_fma_f32 v58, v54, s66, -v62
	v_add_f32_e32 v63, v59, v61
	v_add_f32_e32 v64, v60, v55
	v_fmac_f32_e32 v58, 0xb102e308, v54
	v_sub_f32_e32 v54, v59, v63
	v_sub_f32_e32 v59, v60, v64
	v_rcp_f32_e32 v60, v64
	v_add_f32_e32 v65, v62, v58
	v_add_f32_e32 v55, v55, v59
	v_sub_f32_e32 v59, v65, v62
	v_sub_f32_e32 v58, v58, v59
	v_mul_f32_e32 v59, v63, v60
	v_add_f32_e32 v54, v61, v54
	v_mul_f32_e32 v61, v64, v59
	v_fma_f32 v62, v59, v64, -v61
	v_fmac_f32_e32 v62, v59, v55
	v_add_f32_e32 v77, v61, v62
	v_sub_f32_e32 v78, v63, v77
	v_sub_f32_e32 v61, v77, v61
	v_sub_f32_e32 v63, v63, v78
	v_sub_f32_e32 v61, v61, v62
	v_sub_f32_e32 v62, v63, v77
	v_add_f32_e32 v54, v54, v62
	v_add_f32_e32 v54, v61, v54
	v_add_f32_e32 v61, v78, v54
	v_mul_f32_e32 v62, v60, v61
	v_sub_f32_e32 v63, v78, v61
	v_mul_f32_e32 v77, v64, v62
	v_add_f32_e32 v54, v54, v63
	v_add_f32_e32 v63, v59, v62
	v_fma_f32 v64, v62, v64, -v77
	v_sub_f32_e32 v59, v63, v59
	v_fmac_f32_e32 v64, v62, v55
	v_sub_f32_e32 v55, v62, v59
	v_add_f32_e32 v59, v77, v64
	v_sub_f32_e32 v62, v59, v77
	v_sub_f32_e32 v77, v61, v59
	v_sub_f32_e32 v61, v61, v77
	v_sub_f32_e32 v59, v61, v59
	v_sub_f32_e32 v62, v62, v64
	v_add_f32_e32 v54, v54, v59
	v_add_f32_e32 v54, v62, v54
	v_add_f32_e32 v54, v77, v54
	v_mul_f32_e32 v54, v60, v54
	v_add_f32_e32 v54, v55, v54
	v_add_f32_e32 v55, v63, v54
	v_mul_f32_e32 v59, v55, v55
	v_fmamk_f32 v62, v59, 0x3e9b6dac, v75
	v_sub_f32_e32 v60, v55, v63
	v_ldexp_f32 v61, v55, 1
	v_mul_f32_e32 v55, v55, v59
	v_fmaak_f32 v59, v59, v62, 0x3f2aaada
	v_mul_f32_e32 v55, v55, v59
	v_add_f32_e32 v59, v61, v55
	v_sub_f32_e32 v54, v54, v60
	v_sub_f32_e32 v60, v59, v61
	v_ldexp_f32 v54, v54, 1
	v_sub_f32_e32 v55, v55, v60
	v_add_f32_e32 v54, v54, v55
	v_add_f32_e32 v55, v59, v54
	v_sub_f32_e32 v59, v55, v59
	v_add_f32_e32 v60, v65, v55
	v_sub_f32_e32 v54, v54, v59
	v_sub_f32_e32 v59, v60, v65
	v_sub_f32_e32 v61, v60, v59
	v_sub_f32_e32 v55, v55, v59
	v_add_f32_e32 v59, v58, v54
	v_sub_f32_e32 v61, v65, v61
	v_sub_f32_e32 v62, v59, v58
	v_add_f32_e32 v55, v55, v61
	v_sub_f32_e32 v61, v59, v62
	v_sub_f32_e32 v54, v54, v62
	v_sub_f32_e32 v58, v58, v61
	v_add_f32_e32 v55, v59, v55
	v_add_f32_e32 v54, v54, v58
	v_add_f32_e32 v58, v60, v55
	v_sub_f32_e32 v59, v58, v60
	v_sub_f32_e32 v55, v55, v59
	v_add_f32_e32 v54, v54, v55
	v_add_f32_e32 v54, v58, v54
	v_cmp_neq_f32_e32 vcc, s64, v57
	s_nop 1
	v_cndmask_b32_e32 v54, v76, v54, vcc
	v_cmp_lt_f32_e64 vcc, |v57|, s67
	s_nop 1
	v_cndmask_b32_e32 v54, v54, v57, vcc
	v_sub_f32_e32 v54, v56, v54
	global_store_dword v[34:35], v54, off offset:16
.LBB0_28:
	s_or_b64 exec, exec, s[26:27]
	s_and_saveexec_b64 s[26:27], s[4:5]
	s_cbranch_execz .LBB0_25
	v_pk_mul_f32 v[34:35], v[32:33], v[32:33]
	s_waitcnt lgkmcnt(0)
	v_pk_mul_f32 v[36:37], v[30:31], v[30:31]
	s_nop 0
	v_pk_mov_b32 v[38:39], v[36:37], v[34:35] op_sel:[1,0]
	v_mov_b32_e32 v37, v35
	v_pk_add_f32 v[34:35], v[38:39], v[36:37]
	v_pk_mul_f32 v[36:37], v[28:29], v[28:29]
	v_pk_mul_f32 v[38:39], v[26:27], v[26:27]
	v_pk_add_f32 v[34:35], v[34:35], v[34:35] op_sel:[0,1] op_sel_hi:[1,0]
	v_pk_mov_b32 v[40:41], v[38:39], v[36:37] op_sel:[1,0]
	v_mov_b32_e32 v39, v37
	v_pk_add_f32 v[36:37], v[40:41], v[38:39]
	v_mul_f32_e32 v38, v18, v18
	v_mul_f32_e32 v39, v19, v19
	v_pk_add_f32 v[36:37], v[36:37], v[36:37] op_sel:[0,1] op_sel_hi:[1,0]
	v_mov_b32_e32 v35, v38
	v_mov_b32_e32 v37, v39
	v_pk_add_f32 v[34:35], v[34:35], v[36:37]
	v_mul_f32_e32 v36, v23, v23
	v_mul_f32_e32 v38, v25, v25
	v_mul_f32_e32 v40, v20, v20
	v_mul_f32_e32 v41, v21, v21
	v_pk_fma_f32 v[36:37], v[22:23], v[22:23], v[36:37] op_sel_hi:[1,1,0]
	v_pk_fma_f32 v[38:39], v[24:25], v[24:25], v[38:39] op_sel_hi:[1,1,0]
	v_mov_b32_e32 v37, v40
	v_mov_b32_e32 v39, v41
	v_pk_add_f32 v[36:37], v[36:37], v[38:39]
	s_nop 0
	v_pk_add_f32 v[34:35], v[34:35], v[36:37]
	v_lshl_add_u64 v[36:37], s[74:75], 0, v[48:49]
	v_add_f32_e32 v34, v34, v35
	ds_bpermute_b32 v35, v66, v34
	s_waitcnt lgkmcnt(0)
	v_add_f32_e32 v34, v34, v35
	ds_bpermute_b32 v35, v67, v34
	s_waitcnt lgkmcnt(0)
	v_add_f32_e32 v34, v34, v35
	ds_bpermute_b32 v35, v68, v34
	s_waitcnt lgkmcnt(0)
	v_add_f32_e32 v34, v34, v35
	ds_bpermute_b32 v35, v69, v34
	s_waitcnt lgkmcnt(0)
	v_add_f32_e32 v34, v34, v35
	ds_bpermute_b32 v35, v70, v34
	s_waitcnt lgkmcnt(0)
	v_add_f32_e32 v34, v34, v35
	ds_bpermute_b32 v35, v71, v34
	s_waitcnt lgkmcnt(0)
	v_add_f32_e32 v34, v34, v35
	v_fmamk_f32 v34, v34, 0x3a800000, v74
	v_mul_f32_e32 v35, 0x4b800000, v34
	v_cmp_gt_f32_e32 vcc, s28, v34
	s_nop 1
	v_cndmask_b32_e32 v34, v34, v35, vcc
	v_rsq_f32_e32 v34, v34
	s_nop 0
	v_mul_f32_e32 v35, 0x45800000, v34
	v_cndmask_b32_e32 v38, v34, v35, vcc
	v_pk_mul_f32 v[30:31], v[30:31], v[38:39] op_sel_hi:[1,0]
	v_pk_mul_f32 v[32:33], v[32:33], v[38:39] op_sel_hi:[1,0]
	v_pk_mul_f32 v[34:35], v[2:3], v[30:31]
	v_add_co_u32_e32 v30, vcc, s29, v36
	v_pk_mul_f32 v[32:33], v[4:5], v[32:33]
	s_nop 0
	v_addc_co_u32_e32 v31, vcc, 0, v37, vcc
	v_pk_mul_f32 v[36:37], v[26:27], v[38:39] op_sel_hi:[1,0]
	v_pk_mul_f32 v[26:27], v[28:29], v[38:39] op_sel_hi:[1,0]
	v_cvt_pk_bf16_f32 v40, v34, v35
	v_cvt_pk_bf16_f32 v41, v32, v33
	global_store_dwordx2 v[30:31], v[40:41], off
	v_pk_mul_f32 v[26:27], v[8:9], v[26:27]
	v_pk_mul_f32 v[28:29], v[6:7], v[36:37]
	v_pk_mul_f32 v[18:19], v[18:19], v[38:39] op_sel_hi:[1,0]
	v_cvt_pk_bf16_f32 v36, v28, v29
	v_cvt_pk_bf16_f32 v37, v26, v27
	global_store_dwordx2 v[30:31], v[36:37], off offset:512
	v_pk_mul_f32 v[36:37], v[22:23], v[38:39] op_sel_hi:[1,0]
	v_pk_mul_f32 v[22:23], v[24:25], v[38:39] op_sel_hi:[1,0]
	v_pk_mul_f32 v[24:25], v[10:11], v[36:37]
	v_pk_mul_f32 v[22:23], v[12:13], v[22:23]
	v_cvt_pk_bf16_f32 v36, v24, v25
	v_pk_mul_f32 v[20:21], v[20:21], v[38:39] op_sel_hi:[1,0]
	v_cvt_pk_bf16_f32 v37, v22, v23
	global_store_dwordx2 v[30:31], v[36:37], off offset:1024
	v_pk_mul_f32 v[20:21], v[16:17], v[20:21]
	v_pk_mul_f32 v[36:37], v[14:15], v[18:19]
	s_nop 0
	v_cvt_pk_bf16_f32 v18, v36, v37
	v_cvt_pk_bf16_f32 v19, v20, v21
	ds_read_b128 v[38:41], v1
	ds_read_b128 v[54:57], v1 offset:1024
	global_store_dwordx2 v[30:31], v[18:19], off offset:1536
	ds_read_b128 v[78:81], v1 offset:21504
	s_waitcnt lgkmcnt(2)
	v_mul_f32_e32 v39, v35, v39
	v_fmac_f32_e32 v39, v34, v38
	v_mul_f32_e32 v38, v33, v41
	v_fmac_f32_e32 v38, v32, v40
	v_add_f32_e32 v38, v39, v38
	s_waitcnt lgkmcnt(1)
	v_mul_f32_e32 v55, v29, v55
	v_add_f32_e32 v58, 0, v38
	v_fmac_f32_e32 v55, v28, v54
	v_mul_f32_e32 v54, v27, v57
	ds_read_b128 v[38:41], v1 offset:2048
	v_fmac_f32_e32 v54, v26, v56
	v_add_f32_e32 v54, v55, v54
	v_add_f32_e32 v58, v58, v54
	ds_read_b128 v[54:57], v1 offset:3072
	s_waitcnt lgkmcnt(1)
	v_mul_f32_e32 v39, v25, v39
	v_fmac_f32_e32 v39, v24, v38
	v_mul_f32_e32 v38, v23, v41
	v_fmac_f32_e32 v38, v22, v40
	v_add_f32_e32 v38, v39, v38
	s_waitcnt lgkmcnt(0)
	v_mul_f32_e32 v39, v37, v55
	v_mul_f32_e32 v40, v21, v57
	v_fmac_f32_e32 v39, v36, v54
	v_fmac_f32_e32 v40, v20, v56
	v_add_f32_e32 v38, v58, v38
	v_add_f32_e32 v39, v39, v40
	v_add_f32_e32 v54, v38, v39
	ds_bpermute_b32 v55, v66, v54
	ds_read_b128 v[38:41], v1 offset:4096
	v_mul_f32_e32 v77, v27, v81
	v_fmac_f32_e32 v77, v26, v80
	s_waitcnt lgkmcnt(1)
	v_add_f32_e32 v58, v54, v55
	ds_read_b128 v[54:57], v1 offset:5120
	s_waitcnt lgkmcnt(1)
	v_mul_f32_e32 v39, v35, v39
	v_fmac_f32_e32 v39, v34, v38
	v_mul_f32_e32 v38, v33, v41
	v_fmac_f32_e32 v38, v32, v40
	v_add_f32_e32 v38, v39, v38
	s_waitcnt lgkmcnt(0)
	v_mul_f32_e32 v55, v29, v55
	v_add_f32_e32 v60, 0, v38
	v_fmac_f32_e32 v55, v28, v54
	v_mul_f32_e32 v54, v27, v57
	ds_read_b128 v[38:41], v1 offset:6144
	v_fmac_f32_e32 v54, v26, v56
	v_add_f32_e32 v54, v55, v54
	v_add_f32_e32 v60, v60, v54
	ds_read_b128 v[54:57], v1 offset:7168
	s_waitcnt lgkmcnt(1)
	v_mul_f32_e32 v39, v25, v39
	v_fmac_f32_e32 v39, v24, v38
	v_mul_f32_e32 v38, v23, v41
	v_fmac_f32_e32 v38, v22, v40
	v_add_f32_e32 v38, v39, v38
	s_waitcnt lgkmcnt(0)
	v_mul_f32_e32 v39, v37, v55
	v_mul_f32_e32 v40, v21, v57
	ds_bpermute_b32 v59, v67, v58
	v_fmac_f32_e32 v39, v36, v54
	v_fmac_f32_e32 v40, v20, v56
	v_add_f32_e32 v38, v60, v38
	v_add_f32_e32 v39, v39, v40
	v_add_f32_e32 v38, v38, v39
	ds_bpermute_b32 v39, v66, v38
	s_waitcnt lgkmcnt(1)
	v_add_f32_e32 v40, v58, v59
	ds_bpermute_b32 v41, v68, v40
	s_waitcnt lgkmcnt(1)
	v_add_f32_e32 v54, v38, v39
	ds_bpermute_b32 v55, v67, v54
	s_waitcnt lgkmcnt(1)
	v_add_f32_e32 v58, v40, v41
	ds_read_b128 v[38:41], v1 offset:8192
	ds_bpermute_b32 v59, v69, v58
	s_waitcnt lgkmcnt(2)
	v_add_f32_e32 v60, v54, v55
	ds_read_b128 v[54:57], v1 offset:9216
	s_waitcnt lgkmcnt(2)
	v_mul_f32_e32 v39, v35, v39
	v_fmac_f32_e32 v39, v34, v38
	v_mul_f32_e32 v38, v33, v41
	v_fmac_f32_e32 v38, v32, v40
	v_add_f32_e32 v38, v39, v38
	s_waitcnt lgkmcnt(0)
	v_mul_f32_e32 v55, v29, v55
	v_add_f32_e32 v62, 0, v38
	v_fmac_f32_e32 v55, v28, v54
	v_mul_f32_e32 v54, v27, v57
	ds_read_b128 v[38:41], v1 offset:10240
	v_fmac_f32_e32 v54, v26, v56
	v_add_f32_e32 v54, v55, v54
	v_add_f32_e32 v62, v62, v54
	ds_read_b128 v[54:57], v1 offset:11264
	s_waitcnt lgkmcnt(1)
	v_mul_f32_e32 v39, v25, v39
	v_fmac_f32_e32 v39, v24, v38
	v_mul_f32_e32 v38, v23, v41
	v_fmac_f32_e32 v38, v22, v40
	v_add_f32_e32 v38, v39, v38
	s_waitcnt lgkmcnt(0)
	v_mul_f32_e32 v39, v37, v55
	v_mul_f32_e32 v40, v21, v57
	v_fmac_f32_e32 v39, v36, v54
	v_fmac_f32_e32 v40, v20, v56
	v_add_f32_e32 v38, v62, v38
	v_add_f32_e32 v39, v39, v40
	v_add_f32_e32 v38, v38, v39
	ds_bpermute_b32 v61, v68, v60
	ds_bpermute_b32 v39, v66, v38
	v_add_f32_e32 v40, v58, v59
	ds_bpermute_b32 v41, v70, v40
	ds_read_b128 v[54:57], v1 offset:12288
	s_waitcnt lgkmcnt(3)
	v_add_f32_e32 v58, v60, v61
	s_waitcnt lgkmcnt(2)
	v_add_f32_e32 v60, v38, v39
	ds_bpermute_b32 v59, v69, v58
	ds_bpermute_b32 v61, v67, v60
	s_waitcnt lgkmcnt(3)
	v_add_f32_e32 v38, v40, v41
	ds_bpermute_b32 v39, v71, v38
	s_waitcnt lgkmcnt(2)
	v_add_f32_e32 v40, v58, v59
	s_waitcnt lgkmcnt(1)
	v_add_f32_e32 v41, v60, v61
	ds_read_b128 v[58:61], v1 offset:13312
	v_mul_f32_e32 v55, v35, v55
	v_fmac_f32_e32 v55, v34, v54
	v_mul_f32_e32 v54, v33, v57
	v_fmac_f32_e32 v54, v32, v56
	v_add_f32_e32 v54, v55, v54
	s_waitcnt lgkmcnt(0)
	v_mul_f32_e32 v59, v29, v59
	v_add_f32_e32 v63, 0, v54
	v_fmac_f32_e32 v59, v28, v58
	v_mul_f32_e32 v58, v27, v61
	ds_read_b128 v[54:57], v1 offset:14336
	v_fmac_f32_e32 v58, v26, v60
	v_add_f32_e32 v58, v59, v58
	v_add_f32_e32 v63, v63, v58
	ds_read_b128 v[58:61], v1 offset:15360
	s_waitcnt lgkmcnt(1)
	v_mul_f32_e32 v55, v25, v55
	v_fmac_f32_e32 v55, v24, v54
	v_mul_f32_e32 v54, v23, v57
	v_fmac_f32_e32 v54, v22, v56
	v_add_f32_e32 v54, v55, v54
	s_waitcnt lgkmcnt(0)
	v_mul_f32_e32 v59, v37, v59
	v_add_f32_e32 v63, v63, v54
	v_fmac_f32_e32 v59, v36, v58
	v_mul_f32_e32 v58, v21, v61
	ds_read_b128 v[54:57], v1 offset:16384
	v_fmac_f32_e32 v58, v20, v60
	v_add_f32_e32 v58, v59, v58
	v_add_f32_e32 v63, v63, v58
	ds_read_b128 v[58:61], v1 offset:17408
	s_waitcnt lgkmcnt(1)
	v_mul_f32_e32 v55, v35, v55
	v_fmac_f32_e32 v55, v34, v54
	v_mul_f32_e32 v54, v33, v57
	v_fmac_f32_e32 v54, v32, v56
	v_add_f32_e32 v54, v55, v54
	s_waitcnt lgkmcnt(0)
	v_mul_f32_e32 v59, v29, v59
	v_add_f32_e32 v65, 0, v54
	v_fmac_f32_e32 v59, v28, v58
	v_mul_f32_e32 v58, v27, v61
	ds_read_b128 v[54:57], v1 offset:18432
	v_fmac_f32_e32 v58, v26, v60
	v_add_f32_e32 v58, v59, v58
	v_add_f32_e32 v65, v65, v58
	ds_read_b128 v[58:61], v1 offset:19456
	s_waitcnt lgkmcnt(1)
	v_mul_f32_e32 v55, v25, v55
	v_fmac_f32_e32 v55, v24, v54
	v_mul_f32_e32 v54, v23, v57
	v_fmac_f32_e32 v54, v22, v56
	v_add_f32_e32 v54, v55, v54
	s_waitcnt lgkmcnt(0)
	v_mul_f32_e32 v55, v37, v59
	v_mul_f32_e32 v56, v21, v61
	v_fmac_f32_e32 v55, v36, v58
	v_fmac_f32_e32 v56, v20, v60
	v_add_f32_e32 v54, v65, v54
	v_add_f32_e32 v55, v55, v56
	v_add_f32_e32 v54, v54, v55
	ds_bpermute_b32 v64, v66, v63
	ds_bpermute_b32 v55, v66, v54
	ds_bpermute_b32 v62, v68, v41
	ds_bpermute_b32 v56, v70, v40
	s_waitcnt lgkmcnt(3)
	v_add_f32_e32 v57, v63, v64
	s_waitcnt lgkmcnt(2)
	v_add_f32_e32 v54, v54, v55
	ds_bpermute_b32 v58, v67, v57
	ds_bpermute_b32 v55, v67, v54
	s_waitcnt lgkmcnt(3)
	v_add_f32_e32 v41, v41, v62
	ds_bpermute_b32 v59, v69, v41
	s_waitcnt lgkmcnt(3)
	v_add_f32_e32 v40, v40, v56
	s_waitcnt lgkmcnt(2)
	v_add_f32_e32 v57, v57, v58
	s_waitcnt lgkmcnt(1)
	v_add_f32_e32 v54, v54, v55
	ds_bpermute_b32 v58, v68, v57
	ds_bpermute_b32 v55, v68, v54
	s_waitcnt lgkmcnt(2)
	v_add_f32_e32 v41, v41, v59
	ds_read_b128 v[60:63], v1 offset:20480
	s_waitcnt lgkmcnt(2)
	v_add_f32_e32 v56, v57, v58
	s_waitcnt lgkmcnt(1)
	v_add_f32_e32 v54, v54, v55
	ds_bpermute_b32 v57, v69, v56
	ds_bpermute_b32 v59, v69, v54
	s_waitcnt lgkmcnt(2)
	v_mul_f32_e32 v61, v35, v61
	v_fmac_f32_e32 v61, v34, v60
	v_mul_f32_e32 v60, v33, v63
	s_waitcnt lgkmcnt(1)
	v_add_f32_e32 v56, v56, v57
	s_waitcnt lgkmcnt(0)
	v_add_f32_e32 v64, v54, v59
	ds_bpermute_b32 v57, v70, v56
	ds_bpermute_b32 v65, v70, v64
	v_fmac_f32_e32 v60, v32, v62
	v_add_f32_e32 v60, v61, v60
	ds_bpermute_b32 v58, v70, v41
	s_waitcnt lgkmcnt(2)
	v_add_f32_e32 v54, v56, v57
	s_waitcnt lgkmcnt(1)
	v_add_f32_e32 v56, v64, v65
	v_add_f32_e32 v64, 0, v60
	ds_read_b128 v[60:63], v1 offset:22528
	v_mul_f32_e32 v65, v29, v79
	v_fmac_f32_e32 v65, v28, v78
	ds_read_b128 v[78:81], v1 offset:23552
	v_add_f32_e32 v65, v65, v77
	s_waitcnt lgkmcnt(1)
	v_mul_f32_e32 v61, v25, v61
	v_fmac_f32_e32 v61, v24, v60
	v_mul_f32_e32 v60, v23, v63
	v_fmac_f32_e32 v60, v22, v62
	v_add_f32_e32 v64, v64, v65
	v_add_f32_e32 v60, v61, v60
	v_add_f32_e32 v64, v64, v60
	ds_read_b128 v[60:63], v1 offset:24576
	s_waitcnt lgkmcnt(1)
	v_mul_f32_e32 v65, v37, v79
	v_mul_f32_e32 v77, v21, v81
	v_fmac_f32_e32 v65, v36, v78
	v_fmac_f32_e32 v77, v20, v80
	ds_read_b128 v[78:81], v1 offset:25600
	s_waitcnt lgkmcnt(1)
	v_mul_f32_e32 v61, v35, v61
	v_fmac_f32_e32 v61, v34, v60
	v_mul_f32_e32 v60, v33, v63
	v_fmac_f32_e32 v60, v32, v62
	s_waitcnt lgkmcnt(0)
	v_mul_f32_e32 v79, v29, v79
	v_add_f32_e32 v60, v61, v60
	v_fmac_f32_e32 v79, v28, v78
	v_mul_f32_e32 v78, v27, v81
	v_add_f32_e32 v65, v65, v77
	v_add_f32_e32 v77, 0, v60
	ds_read_b128 v[60:63], v1 offset:26624
	v_fmac_f32_e32 v78, v26, v80
	v_add_f32_e32 v78, v79, v78
	v_add_f32_e32 v77, v77, v78
	ds_read_b128 v[78:81], v1 offset:27648
	s_waitcnt lgkmcnt(1)
	v_mul_f32_e32 v61, v25, v61
	v_fmac_f32_e32 v61, v24, v60
	v_mul_f32_e32 v60, v23, v63
	v_fmac_f32_e32 v60, v22, v62
	s_waitcnt lgkmcnt(0)
	v_mul_f32_e32 v79, v37, v79
	v_add_f32_e32 v60, v61, v60
	v_fmac_f32_e32 v79, v36, v78
	v_mul_f32_e32 v78, v21, v81
	v_add_f32_e32 v77, v77, v60
	v_fmac_f32_e32 v78, v20, v80
	ds_read_b128 v[60:63], v1 offset:28672
	v_add_f32_e32 v78, v79, v78
	v_add_f32_e32 v77, v77, v78
	ds_read_b128 v[78:81], v1 offset:29696
	v_add_f32_e32 v64, v64, v65
	s_waitcnt lgkmcnt(1)
	v_mul_f32_e32 v35, v35, v61
	v_mul_f32_e32 v33, v33, v63
	v_fmac_f32_e32 v35, v34, v60
	v_fmac_f32_e32 v33, v32, v62
	v_add_f32_e32 v32, v35, v33
	s_waitcnt lgkmcnt(0)
	v_mul_f32_e32 v29, v29, v79
	v_mul_f32_e32 v27, v27, v81
	v_add_f32_e32 v60, 0, v32
	v_fmac_f32_e32 v29, v28, v78
	ds_read_b128 v[32:35], v1 offset:30720
	v_fmac_f32_e32 v27, v26, v80
	v_add_f32_e32 v26, v29, v27
	v_add_f32_e32 v60, v60, v26
	ds_read_b128 v[26:29], v1 offset:31744
	s_waitcnt lgkmcnt(1)
	v_mul_f32_e32 v25, v25, v33
	v_mul_f32_e32 v23, v23, v35
	v_fmac_f32_e32 v25, v24, v32
	v_fmac_f32_e32 v23, v22, v34
	v_add_f32_e32 v22, v25, v23
	s_waitcnt lgkmcnt(0)
	v_mul_f32_e32 v23, v37, v27
	v_mul_f32_e32 v21, v21, v29
	v_fmac_f32_e32 v23, v36, v26
	v_fmac_f32_e32 v21, v20, v28
	v_add_f32_e32 v22, v60, v22
	v_add_f32_e32 v20, v23, v21
	v_add_f32_e32 v20, v22, v20
	ds_bpermute_b32 v65, v66, v64
	ds_bpermute_b32 v82, v66, v77
	ds_bpermute_b32 v21, v66, v20
	v_add_f32_e32 v41, v41, v58
	ds_bpermute_b32 v55, v71, v40
	s_waitcnt lgkmcnt(3)
	v_add_f32_e32 v22, v64, v65
	s_waitcnt lgkmcnt(2)
	v_add_f32_e32 v24, v77, v82
	s_waitcnt lgkmcnt(1)
	v_add_f32_e32 v20, v20, v21
	ds_bpermute_b32 v23, v67, v22
	ds_bpermute_b32 v25, v67, v24
	ds_bpermute_b32 v21, v67, v20
	ds_bpermute_b32 v58, v71, v41
	ds_bpermute_b32 v59, v71, v54
	s_waitcnt lgkmcnt(4)
	v_add_f32_e32 v22, v22, v23
	s_waitcnt lgkmcnt(3)
	v_add_f32_e32 v24, v24, v25
	s_waitcnt lgkmcnt(2)
	v_add_f32_e32 v20, v20, v21
	ds_bpermute_b32 v23, v68, v22
	ds_bpermute_b32 v25, v68, v24
	ds_bpermute_b32 v21, v68, v20
	ds_bpermute_b32 v57, v71, v56
	s_waitcnt lgkmcnt(3)
	v_add_f32_e32 v22, v22, v23
	s_waitcnt lgkmcnt(2)
	v_add_f32_e32 v24, v24, v25
	s_waitcnt lgkmcnt(1)
	v_add_f32_e32 v20, v20, v21
	ds_bpermute_b32 v23, v69, v22
	ds_bpermute_b32 v25, v69, v24
	ds_bpermute_b32 v21, v69, v20
	s_waitcnt lgkmcnt(2)
	v_add_f32_e32 v22, v22, v23
	s_waitcnt lgkmcnt(1)
	v_add_f32_e32 v26, v24, v25
	s_waitcnt lgkmcnt(0)
	v_add_f32_e32 v20, v20, v21
	ds_bpermute_b32 v23, v70, v22
	ds_bpermute_b32 v27, v70, v26
	ds_bpermute_b32 v21, v70, v20
	s_waitcnt lgkmcnt(2)
	v_add_f32_e32 v24, v22, v23
	s_waitcnt lgkmcnt(1)
	v_add_f32_e32 v22, v26, v27
	s_waitcnt lgkmcnt(0)
	v_add_f32_e32 v20, v20, v21
	ds_bpermute_b32 v25, v71, v24
	ds_bpermute_b32 v23, v71, v22
	ds_bpermute_b32 v21, v71, v20
	s_and_b64 exec, exec, s[68:69]
	s_cbranch_execz .LBB0_25
	v_readlane_b32 s36, v254, 5
	v_readlane_b32 s37, v254, 6
	v_lshl_add_u64 v[18:19], s[74:75], 0, v[46:47]
	v_add_f32_e32 v27, v38, v39
	v_add_co_u32_e32 v18, vcc, 0x26a8000, v18
	v_readlane_b32 s38, v254, 7
	s_nop 0
	v_addc_co_u32_e32 v19, vcc, 0, v19, vcc
	v_readlane_b32 s39, v254, 8
	s_waitcnt lgkmcnt(2)
	v_add_f32_e32 v24, v24, v25
	s_waitcnt lgkmcnt(1)
	v_add_f32_e32 v22, v22, v23
	s_waitcnt lgkmcnt(0)
	v_add_f32_e32 v20, v20, v21
	v_readlane_b32 s40, v254, 9
	v_readlane_b32 s41, v254, 10
	v_readlane_b32 s42, v254, 11
	v_readlane_b32 s43, v254, 12
	v_readlane_b32 s44, v254, 13
	v_readlane_b32 s45, v254, 14
	v_readlane_b32 s46, v254, 15
	v_readlane_b32 s47, v254, 16
	v_readlane_b32 s48, v254, 17
	v_readlane_b32 s49, v254, 18
	v_readlane_b32 s50, v254, 19
	v_readlane_b32 s51, v254, 20
	v_add_f32_e32 v28, v40, v55
	v_add_f32_e32 v29, v41, v58
	v_add_f32_e32 v30, v54, v59
	v_cndmask_b32_e64 v27, v27, v28, s[18:19]
	v_cndmask_b32_e64 v27, v27, v29, s[20:21]
	v_cndmask_b32_e64 v27, v27, v30, s[22:23]
	v_add_f32_e32 v26, v110, v27
	v_add_co_u32_e32 v18, vcc, v112, v18
	s_nop 1
	v_addc_co_u32_e32 v19, vcc, 0, v19, vcc
	global_store_dword v[18:19], v26, off
	v_add_f32_e32 v27, v56, v57
	v_cndmask_b32_e64 v27, v27, v24, s[18:19]
	v_cndmask_b32_e64 v27, v27, v22, s[20:21]
	v_cndmask_b32_e64 v27, v27, v20, s[22:23]
	v_add_f32_e32 v26, v111, v27
	s_mov_b64 exec, 0xff
	s_nop 4
	v_mov_b32_dpp v26, v113 row_shr:4 row_mask:0xf bank_mask:0x2
	v_mov_b32_dpp v18, v114 row_shr:4 row_mask:0xf bank_mask:0x2
	v_mov_b32_dpp v19, v115 row_shr:4 row_mask:0xf bank_mask:0x2
	v_mul_f32_e64 v27, |v26|, s30
	v_fma_f32 v28, |v26|, s30, -v27
	v_rndne_f32_e32 v29, v27
	v_fma_f32 v28, |v26|, s31, v28
	v_sub_f32_e32 v27, v27, v29
	v_add_f32_e32 v27, v27, v28
	v_cvt_i32_f32_e32 v29, v29
	v_exp_f32_e32 v27, v27
	v_cmp_ngt_f32_e64 vcc, |v26|, s34
	v_min_f32_e32 v28, 0, v26
	v_ldexp_f32 v27, v27, v29
	v_cndmask_b32_e32 v27, 0, v27, vcc
	v_cmp_nlt_f32_e64 vcc, |v26|, s35
	s_nop 1
	v_cndmask_b32_e32 v29, v76, v27, vcc
	v_add_f32_e32 v30, 1.0, v29
	v_add_f32_e32 v31, -1.0, v30
	v_frexp_mant_f32_e32 v32, v30
	v_cvt_f64_f32_e32 v[26:27], v30
	v_sub_f32_e32 v33, v31, v30
	v_frexp_exp_i32_f64_e32 v26, v[26:27]
	v_cmp_gt_f32_e32 vcc, s65, v32
	v_sub_f32_e32 v31, v29, v31
	v_add_f32_e32 v27, 1.0, v33
	v_subbrev_co_u32_e32 v26, vcc, 0, v26, vcc
	v_add_f32_e32 v27, v31, v27
	v_sub_u32_e32 v31, 0, v26
	v_cvt_f32_i32_e32 v26, v26
	v_ldexp_f32 v30, v30, v31
	v_ldexp_f32 v27, v27, v31
	v_add_f32_e32 v31, -1.0, v30
	v_add_f32_e32 v32, 1.0, v30
	v_add_f32_e32 v33, 1.0, v31
	v_add_f32_e32 v34, -1.0, v32
	v_sub_f32_e32 v33, v30, v33
	v_sub_f32_e32 v30, v30, v34
	v_mul_f32_e32 v34, 0x3f317218, v26
	v_add_f32_e32 v33, v27, v33
	v_add_f32_e32 v27, v27, v30
	v_fma_f32 v30, v26, s66, -v34
	v_add_f32_e32 v35, v31, v33
	v_add_f32_e32 v36, v32, v27
	v_fmac_f32_e32 v30, 0xb102e308, v26
	v_sub_f32_e32 v26, v31, v35
	v_sub_f32_e32 v31, v32, v36
	v_rcp_f32_e32 v32, v36
	v_add_f32_e32 v37, v34, v30
	v_add_f32_e32 v27, v27, v31
	v_sub_f32_e32 v31, v37, v34
	v_sub_f32_e32 v30, v30, v31
	v_mul_f32_e32 v31, v35, v32
	v_add_f32_e32 v26, v33, v26
	v_mul_f32_e32 v33, v36, v31
	v_fma_f32 v34, v31, v36, -v33
	v_fmac_f32_e32 v34, v31, v27
	v_add_f32_e32 v38, v33, v34
	v_sub_f32_e32 v39, v35, v38
	v_sub_f32_e32 v33, v38, v33
	v_sub_f32_e32 v35, v35, v39
	v_sub_f32_e32 v33, v33, v34
	v_sub_f32_e32 v34, v35, v38
	v_add_f32_e32 v26, v26, v34
	v_add_f32_e32 v26, v33, v26
	v_add_f32_e32 v33, v39, v26
	v_mul_f32_e32 v34, v32, v33
	v_sub_f32_e32 v35, v39, v33
	v_mul_f32_e32 v38, v36, v34
	v_add_f32_e32 v26, v26, v35
	v_add_f32_e32 v35, v31, v34
	v_fma_f32 v36, v34, v36, -v38
	v_sub_f32_e32 v31, v35, v31
	v_fmac_f32_e32 v36, v34, v27
	v_sub_f32_e32 v27, v34, v31
	v_add_f32_e32 v31, v38, v36
	v_sub_f32_e32 v34, v31, v38
	v_sub_f32_e32 v38, v33, v31
	v_sub_f32_e32 v33, v33, v38
	v_sub_f32_e32 v31, v33, v31
	v_sub_f32_e32 v34, v34, v36
	v_add_f32_e32 v26, v26, v31
	v_add_f32_e32 v26, v34, v26
	v_add_f32_e32 v26, v38, v26
	v_mul_f32_e32 v26, v32, v26
	v_add_f32_e32 v26, v27, v26
	v_add_f32_e32 v27, v35, v26
	v_mul_f32_e32 v31, v27, v27
	v_fmamk_f32 v34, v31, 0x3e9b6dac, v75
	v_sub_f32_e32 v32, v27, v35
	v_ldexp_f32 v33, v27, 1
	v_mul_f32_e32 v27, v27, v31
	v_fmaak_f32 v31, v31, v34, 0x3f2aaada
	v_mul_f32_e32 v27, v27, v31
	v_add_f32_e32 v31, v33, v27
	v_sub_f32_e32 v26, v26, v32
	v_sub_f32_e32 v32, v31, v33
	v_ldexp_f32 v26, v26, 1
	v_sub_f32_e32 v27, v27, v32
	v_add_f32_e32 v26, v26, v27
	v_add_f32_e32 v27, v31, v26
	v_sub_f32_e32 v31, v27, v31
	v_add_f32_e32 v32, v37, v27
	v_sub_f32_e32 v26, v26, v31
	v_sub_f32_e32 v31, v32, v37
	v_sub_f32_e32 v33, v32, v31
	v_sub_f32_e32 v27, v27, v31
	v_add_f32_e32 v31, v30, v26
	v_sub_f32_e32 v33, v37, v33
	v_sub_f32_e32 v34, v31, v30
	v_add_f32_e32 v27, v27, v33
	v_sub_f32_e32 v33, v31, v34
	v_sub_f32_e32 v26, v26, v34
	v_sub_f32_e32 v30, v30, v33
	v_add_f32_e32 v27, v31, v27
	v_add_f32_e32 v26, v26, v30
	v_add_f32_e32 v30, v32, v27
	v_sub_f32_e32 v31, v30, v32
	v_sub_f32_e32 v27, v27, v31
	v_add_f32_e32 v26, v26, v27
	v_add_f32_e32 v26, v30, v26
	v_cmp_neq_f32_e32 vcc, s64, v29
	s_nop 1
	v_cndmask_b32_e32 v26, v76, v26, vcc
	v_cmp_lt_f32_e64 vcc, |v29|, s67
	s_nop 1
	v_cndmask_b32_e32 v26, v26, v29, vcc
	v_sub_f32_e32 v26, v28, v26
	global_store_dword v[18:19], v26, off offset:16
	s_branch .LBB0_25
